# attention: half-step stagger of waves 4-7 with mid barrier; staging store end of H1, loads start of H2; plus earlier edits
# speedup vs baseline: 1.0138x; 1.0138x over previous
; #define ATT_LOAD(S, t) do { S[0] = *(const GAS v4u*)(gsrc[0] + (size_t)(t) * 64 * NH); S[1] = *(const GAS v4u*)(gsrc[1] + (size_t)(t) * 64 * NH); S[2] = *(const GAS v4u*)(gsrc[2] + (t) * 64); S[3] = *(const GAS v4u*)(gsrc[3] + (t) * 64); } while (0)
; #define ATT_STORE(S, boff) do { _Pragma("unroll") for (int i_ = 0; i_ < 2; ++i_) *(v4u*)(lds + (boff) + ldst[i_]) = S[i_]; \
;     _Pragma("unroll") for (int i_ = 2; i_ < 4; ++i_) { v2u lo_, hi_; lo_.x = S[i_].x; lo_.y = S[i_].y; hi_.x = S[i_].z; hi_.y = S[i_].w; *(v2u*)(lds + (boff) + ldst[i_]) = lo_; *(v2u*)(lds + (boff) + ldst[i_] + 16) = hi_; } } while (0)
; template <bool DO_S, bool DO_PV, bool DIAG>
; __device__ __forceinline__ void attn_step(const char* Ks, const char* Vs, const bf16x8_t (&qf)[2], bf16x8_t (&pf)[2], pg8::f32x4 (&oacc)[8], float& mrun, float& lsum, bool diag, int rs, int li, int g) {
;     ...
;     const char* kp = Ks + li * KROW + g * 16; const char* vp = Vs + li * KROW + g * 16;
;     pg8::f32x4 sacc[4];
;     if (DO_S) {
;         bf16x8_t kf[8];
; #pragma unroll
;         for (int i = 0; i < 8; ++i) kf[i] = *(const bf16x8_t*)(kp + (i >> 1) * 16 * KROW + (i & 1) * 64);
; #pragma unroll
;         for (int kb = 0; kb < 4; ++kb) { sacc[kb] = __builtin_amdgcn_mfma_f32_16x16x32_bf16(kf[2 * kb], qf[0], (pg8::f32x4){0.f, 0.f, 0.f, 0.f}, 0, 0, 0); sacc[kb] = __builtin_amdgcn_mfma_f32_16x16x32_bf16(kf[2 * kb + 1], qf[1], sacc[kb], 0, 0, 0); }
;     }
;     bf16x8_t vf[16];
;     if (DO_PV) {
; #pragma unroll
;         for (int i = 0; i < 16; ++i) vf[i] = *(const bf16x8_t*)(vp + (i >> 1) * 16 * KROW + (i & 1) * 64);
;     }
; __device__ __forceinline__ void mix_attn(const bf16* h, const bf16* VT, const float* dl, int layer, const float* ng, bf16* ycat, char* lds, int wg, int G) {
;     ...
;             for (int t = 0; t < qb; ++t) {
;                 if (t + 2 <= qb) ATT_LOAD(stA, t + 2);
;                 if (t + 1 == qb) attn_step<true, true, true>(lds + b1 + st * K2OFF, lds + b0 + VOFF, qf, pf, oacc, mrun, lsum, true, rs, li, g);
;                 else attn_step<true, true, false>(lds + b1 + st * K2OFF, lds + b0 + VOFF, qf, pf, oacc, mrun, lsum, false, rs, li, g);
;                 if (t + 2 <= qb) ATT_STORE(stA, b2);
;                 __syncthreads();
;                 const int tmp = b0; b0 = b1; b1 = b2; b2 = tmp;
;             }
.LBB0_571:
	s_and_b64 vcc, exec, s[4:5]
	s_waitcnt lgkmcnt(0)
	s_barrier
	s_cbranch_vccnz .LBB0_582
	s_cmp_eq_u32 s79, 1
	s_cbranch_scc1 .LBB0_583
	s_add_i32 s15, s79, -1
	s_mov_b32 s78, 0x14000
	s_mov_b32 s14, 0xa000
	s_mov_b32 s81, 0
	s_movk_i32 s28, 0x80
	v_mov_b64_e32 v[32:33], v[176:177]
	v_mov_b64_e32 v[34:35], v[174:175]
	s_mov_b32 s80, 0
	s_lshl_b64 s[82:83], s[28:29], 1
	v_lshl_add_u64 v[36:37], v[186:187], 0, s[82:83]
	global_load_dwordx4 v[64:67], v[32:33], off
	global_load_dwordx4 v[68:71], v[34:35], off
	v_lshl_add_u64 v[38:39], v[188:189], 0, s[82:83]
	global_load_dwordx4 v[72:75], v[36:37], off
	global_load_dwordx4 v[76:79], v[38:39], off
	s_andn2_b64 vcc, exec, s[74:75]
	s_cbranch_vccnz .Lattn_stag_in
	s_barrier
.Lattn_stag_in:
.LBB0_574:
	s_mov_b32 s1, s81
.LBB0_576:
	v_add_u32_e32 v96, s14, v225
	ds_read_b128 v[36:39], v96
	ds_read_b128 v[40:43], v96 offset:64
	ds_read_b128 v[44:47], v96 offset:2560
	ds_read_b128 v[48:51], v96 offset:2624
	ds_read_b128 v[52:55], v96 offset:5120
	ds_read_b128 v[60:63], v96 offset:7680
	ds_read_b128 v[56:59], v96 offset:5184
	ds_read_b128 v[96:99], v96 offset:7744
	s_waitcnt lgkmcnt(7)
	v_mfma_f32_16x16x32_bf16 v[36:39], v[36:39], v[80:83], 0
	s_waitcnt lgkmcnt(6)
	v_mfma_f32_16x16x32_bf16 v[38:41], v[40:43], v[84:87], v[36:39]
	s_waitcnt lgkmcnt(5)
	v_mfma_f32_16x16x32_bf16 v[42:45], v[44:47], v[80:83], 0
	s_nop 3
	v_add_u32_e32 v36, s1, v155
	ds_read_b128 v[100:103], v36 offset:23104
	ds_read_b128 v[104:107], v36 offset:25600
	s_waitcnt lgkmcnt(6)
	v_mfma_f32_16x16x32_bf16 v[42:45], v[48:51], v[84:87], v[42:45]
	ds_read_b128 v[108:111], v36 offset:25664
	ds_read_b128 v[112:115], v36 offset:28160
	ds_read_b128 v[116:119], v36 offset:28224
	s_waitcnt lgkmcnt(8)
	v_mfma_f32_16x16x32_bf16 v[46:49], v[52:55], v[80:83], 0
	ds_read_b128 v[120:123], v36 offset:30720
	ds_read_b128 v[124:127], v36 offset:30784
	ds_read_b128 v[128:131], v36 offset:33280
	s_waitcnt lgkmcnt(10)
	v_mfma_f32_16x16x32_bf16 v[50:53], v[60:63], v[80:83], 0
	ds_read_b128 v[132:135], v36 offset:33344
	ds_read_b128 v[136:139], v36 offset:35840
	ds_read_b128 v[200:203], v36 offset:35904
	s_waitcnt lgkmcnt(12)
	v_mfma_f32_16x16x32_bf16 v[46:49], v[56:59], v[84:87], v[46:49]
	ds_read_b128 v[54:57], v36 offset:20480
	ds_read_b128 v[58:61], v36 offset:20544
	ds_read_b128 v[204:207], v36 offset:38400
	s_waitcnt lgkmcnt(14)
	v_mfma_f32_16x16x32_bf16 v[50:53], v[96:99], v[84:87], v[50:53]
	ds_read_b128 v[96:99], v36 offset:23040
	ds_read_b128 v[208:211], v36 offset:38464
	s_add_i32 s4, s78, 0
	v_add_u32_e32 v62, s4, v148
	s_waitcnt vmcnt(3)
	ds_write_b128 v62, v[64:67]
	v_add_u32_e32 v62, s4, v152
	s_waitcnt vmcnt(2)
	ds_write_b128 v62, v[68:71]
	v_add_u32_e32 v62, s4, v154
	v_add_u32_e32 v62, 0x5000, v62
	s_waitcnt vmcnt(1)
	ds_write2_b64 v62, v[72:73], v[74:75] offset1:2
	v_add_u32_e32 v62, s4, v156
	v_add_u32_e32 v62, 0x5000, v62
	s_waitcnt vmcnt(0)
	ds_write2_b64 v62, v[76:77], v[78:79] offset1:2
	s_waitcnt lgkmcnt(0)
	s_barrier
	s_add_i32 s4, s80, 3
	s_cmp_gt_i32 s4, s79
	s_cbranch_scc1 .Lattn_stag_noload
	s_add_i32 s82, s28, 64
	s_lshl_b32 s82, s82, 1
	s_mov_b32 s83, 0
	v_lshl_add_u64 v[62:63], v[32:33], 0, s[34:35]
	global_load_dwordx4 v[64:67], v[62:63], off
	v_lshl_add_u64 v[62:63], v[34:35], 0, s[34:35]
	global_load_dwordx4 v[68:71], v[62:63], off
	v_lshl_add_u64 v[62:63], v[186:187], 0, s[82:83]
	global_load_dwordx4 v[72:75], v[62:63], off
	v_lshl_add_u64 v[62:63], v[188:189], 0, s[82:83]
	global_load_dwordx4 v[76:79], v[62:63], off
; template <bool DO_S, bool DO_PV, bool DIAG>
; __device__ __forceinline__ void attn_step(const char* Ks, const char* Vs, const bf16x8_t (&qf)[2], bf16x8_t (&pf)[2], pg8::f32x4 (&oacc)[8], float& mrun, float& lsum, bool diag, int rs, int li, int g) {
;     ...
;     __builtin_amdgcn_sched_barrier(0);
;     const bf16x8_t p0 = pf[0], p1 = pf[1];
;     if (DO_PV) {
; #pragma unroll
;         for (int i = 0; i < 16; ++i) oacc[i >> 1] = __builtin_amdgcn_mfma_f32_16x16x32_bf16(vf[i], (i & 1) ? p1 : p0, oacc[i >> 1], 0, 0, 0);
;     }
;     float alpha = 1.f; bool grow = false;
;     if (DO_S) {
;         float mx = -INFINITY;
; #pragma unroll
;         for (int kb = 0; kb < 4; ++kb)
; #pragma unroll
;             for (int r = 0; r < 4; ++r) { float sv = sacc[kb][r]; if (DIAG && (16 * kb + 4 * g + r) > (16 * rs + li)) sv = -INFINITY; sacc[kb][r] = sv; mx = fmaxf(mx, sv); }
;         mx = xmax16_32(mx);
;         grow = mx > mrun + 8.0f / SC; const float mnew = grow ? mx : mrun; alpha = __builtin_amdgcn_exp2f((mrun - mnew) * SC); mrun = mnew;
;         const float nm = -mnew * SC; pg8::f32x4 psv = (pg8::f32x4){0.f, 0.f, 0.f, 0.f};
; #pragma unroll
;         for (int kb = 0; kb < 4; ++kb) { pg8::f32x4 tt = sacc[kb] * SC + nm;
;             tt[0] = __builtin_amdgcn_exp2f(tt[0]); tt[1] = __builtin_amdgcn_exp2f(tt[1]); tt[2] = __builtin_amdgcn_exp2f(tt[2]); tt[3] = __builtin_amdgcn_exp2f(tt[3]); sacc[kb] = tt; psv += tt; }
;         const float ps = (psv[0] + psv[1]) + (psv[2] + psv[3]);
;         lsum = lsum * alpha + ps;
; #pragma unroll
;         for (int ks = 0; ks < 2; ++ks) { v4u w; w.x = pg8::cvt_pk_bf16(sacc[2 * ks][0], sacc[2 * ks][1]); w.y = pg8::cvt_pk_bf16(sacc[2 * ks][2], sacc[2 * ks][3]);
;             w.z = pg8::cvt_pk_bf16(sacc[2 * ks + 1][0], sacc[2 * ks + 1][1]); w.w = pg8::cvt_pk_bf16(sacc[2 * ks + 1][2], sacc[2 * ks + 1][3]); pf[ks] = __builtin_bit_cast(bf16x8_t, w); }
;     }
;     if (DO_S && DO_PV) {
; #pragma unroll
;         for (int i = 0; i < 16; ++i) { __builtin_amdgcn_sched_group_barrier(0x008, 1, 0); __builtin_amdgcn_sched_group_barrier(0x002, 7, 0); }
;     }
;     __builtin_amdgcn_sched_barrier(0);
;     if (DO_S) { if (__any(grow)) {
; #pragma unroll
;         for (int i = 0; i < 8; ++i) oacc[i] = oacc[i] * alpha; }
;     }
.Lattn_stag_noload:
	s_waitcnt lgkmcnt(4)
	v_mfma_f32_16x16x32_bf16 v[0:3], v[54:57], v[88:91], v[0:3]
	v_max3_f32 v36, v38, s33, v39
	v_max3_f32 v36, v36, v40, v41
	v_max3_f32 v36, v36, v42, v43
	v_max3_f32 v36, v36, v44, v45
	v_max3_f32 v36, v36, v46, v47
	v_max3_f32 v36, v36, v48, v49
	v_max3_f32 v36, v36, v50, v51
	s_waitcnt lgkmcnt(3)
	v_mfma_f32_16x16x32_bf16 v[0:3], v[58:61], v[92:95], v[0:3]
	v_max3_f32 v36, v36, v52, v53
	v_mov_b32_e32 v37, v36
	s_nop 1
	v_permlane16_swap_b32_e32 v36, v37
	v_max_f32_e32 v37, v37, v37
	v_max_f32_e32 v36, v36, v36
	v_max_f32_e32 v36, v36, v37
	v_mov_b32_e32 v37, v36
	s_waitcnt lgkmcnt(1)
	v_mfma_f32_16x16x32_bf16 v[4:7], v[96:99], v[88:91], v[4:7]
	v_permlane32_swap_b32_e32 v36, v37
	v_max_f32_e32 v37, v37, v37
	v_max_f32_e32 v36, v36, v36
	v_max_f32_e32 v36, v36, v37
	v_add_f32_e32 v37, 0x42317218, v165
	v_cmp_gt_f32_e32 vcc, v36, v37
	s_nop 1
	v_cndmask_b32_e32 v37, v165, v36, vcc
	v_mfma_f32_16x16x32_bf16 v[4:7], v[100:103], v[92:95], v[4:7]
	v_sub_f32_e32 v36, v165, v37
	v_mul_f32_e32 v60, 0x3e38aa3b, v36
	v_mul_f32_e32 v36, 0xbe38aa3b, v37
	v_fma_f32 v40, v40, s10, v36
	v_fma_f32 v41, v41, s10, v36
	v_fma_f32 v38, v38, s10, v36
	v_fma_f32 v39, v39, s10, v36
	v_fma_f32 v44, v44, s10, v36
	v_fma_f32 v45, v45, s10, v36
	v_fma_f32 v42, v42, s10, v36
	v_fma_f32 v43, v43, s10, v36
	v_mfma_f32_16x16x32_bf16 v[8:11], v[104:107], v[88:91], v[8:11]
	v_fma_f32 v54, v48, s10, v36
	v_fma_f32 v55, v49, s10, v36
	v_fma_f32 v56, v46, s10, v36
	v_fma_f32 v57, v47, s10, v36
	v_fma_f32 v58, v52, s10, v36
	v_fma_f32 v59, v53, s10, v36
	v_fma_f32 v50, v50, s10, v36
	v_fma_f32 v51, v51, s10, v36
	v_mfma_f32_16x16x32_bf16 v[8:11], v[108:111], v[92:95], v[8:11]
	v_exp_f32_e32 v48, v38
	v_exp_f32_e32 v49, v39
	v_exp_f32_e32 v46, v40
	v_mfma_f32_16x16x32_bf16 v[12:15], v[112:115], v[88:91], v[12:15]
	v_exp_f32_e32 v47, v41
	v_exp_f32_e32 v40, v42
	v_exp_f32_e32 v41, v43
	v_mfma_f32_16x16x32_bf16 v[12:15], v[116:119], v[92:95], v[12:15]
	v_exp_f32_e32 v52, v44
	v_exp_f32_e32 v53, v45
	v_exp_f32_e32 v44, v56
	v_mfma_f32_16x16x32_bf16 v[16:19], v[120:123], v[88:91], v[16:19]
	v_exp_f32_e32 v45, v57
	v_exp_f32_e32 v42, v54
	v_exp_f32_e32 v43, v55
	v_mfma_f32_16x16x32_bf16 v[16:19], v[124:127], v[92:95], v[16:19]
	v_exp_f32_e32 v38, v50
	v_exp_f32_e32 v39, v51
	v_exp_f32_e32 v50, v58
	v_mfma_f32_16x16x32_bf16 v[20:23], v[128:131], v[88:91], v[20:23]
	v_exp_f32_e32 v51, v59
	v_exp_f32_e32 v36, v60
	v_mfma_f32_16x16x32_bf16 v[20:23], v[132:135], v[92:95], v[20:23]
	v_mfma_f32_16x16x32_bf16 v[24:27], v[136:139], v[88:91], v[24:27]
	v_mfma_f32_16x16x32_bf16 v[24:27], v[200:203], v[92:95], v[24:27]
	v_mfma_f32_16x16x32_bf16 v[28:31], v[204:207], v[88:91], v[28:31]
	v_cvt_pk_bf16_f32 v88, v48, v49
	v_cvt_pk_bf16_f32 v89, v46, v47
	v_cvt_pk_bf16_f32 v90, v40, v41
	s_waitcnt lgkmcnt(0)
	v_mfma_f32_16x16x32_bf16 v[28:31], v[208:211], v[92:95], v[28:31]
	v_cvt_pk_bf16_f32 v91, v52, v53
	v_cvt_pk_bf16_f32 v92, v44, v45
	v_cvt_pk_bf16_f32 v93, v42, v43
	v_cvt_pk_bf16_f32 v94, v38, v39
	v_cvt_pk_bf16_f32 v95, v50, v51
	s_cbranch_vccz .LBB0_578
	s_nop 6
	v_pk_mul_f32 v[30:31], v[30:31], v[36:37] op_sel_hi:[1,0]
	v_pk_mul_f32 v[26:27], v[26:27], v[36:37] op_sel_hi:[1,0]
	v_pk_mul_f32 v[22:23], v[22:23], v[36:37] op_sel_hi:[1,0]
	v_pk_mul_f32 v[18:19], v[18:19], v[36:37] op_sel_hi:[1,0]
	v_pk_mul_f32 v[14:15], v[14:15], v[36:37] op_sel_hi:[1,0]
	v_pk_mul_f32 v[10:11], v[10:11], v[36:37] op_sel_hi:[1,0]
	v_pk_mul_f32 v[6:7], v[6:7], v[36:37] op_sel_hi:[1,0]
	v_pk_mul_f32 v[2:3], v[2:3], v[36:37] op_sel_hi:[1,0]
	v_pk_mul_f32 v[28:29], v[28:29], v[36:37] op_sel_hi:[1,0]
	v_pk_mul_f32 v[24:25], v[24:25], v[36:37] op_sel_hi:[1,0]
	v_pk_mul_f32 v[20:21], v[20:21], v[36:37] op_sel_hi:[1,0]
	v_pk_mul_f32 v[16:17], v[16:17], v[36:37] op_sel_hi:[1,0]
	v_pk_mul_f32 v[12:13], v[12:13], v[36:37] op_sel_hi:[1,0]
	v_pk_mul_f32 v[8:9], v[8:9], v[36:37] op_sel_hi:[1,0]
	v_pk_mul_f32 v[4:5], v[4:5], v[36:37] op_sel_hi:[1,0]
	v_pk_mul_f32 v[0:1], v[0:1], v[36:37] op_sel_hi:[1,0]
.LBB0_578:
.LBB0_580:
	v_add_f32_e32 v48, 0, v48
	v_add_f32_e32 v49, 0, v49
	v_add_f32_e32 v46, 0, v46
	v_add_f32_e32 v47, 0, v47
	v_add_f32_e32 v40, v40, v48
	v_add_f32_e32 v41, v41, v49
	v_add_f32_e32 v46, v52, v46
	v_add_f32_e32 v47, v53, v47
	v_add_f32_e32 v40, v44, v40
	v_add_f32_e32 v41, v45, v41
	v_add_f32_e32 v42, v42, v46
	v_add_f32_e32 v43, v43, v47
	v_add_f32_e32 v38, v38, v40
	v_add_f32_e32 v39, v39, v41
	v_add_f32_e32 v42, v50, v42
	v_add_f32_e32 v43, v51, v43
	v_add_f32_e32 v38, v38, v39
	v_add_f32_e32 v39, v42, v43
	s_add_i32 s80, s80, 1
	v_add_f32_e32 v96, v38, v39
	s_add_i32 s28, s28, 64
	v_fmac_f32_e32 v96, v157, v36
	v_lshl_add_u64 v[34:35], v[34:35], 0, s[34:35]
	s_cmp_eq_u32 s15, s80
	v_lshl_add_u64 v[32:33], v[32:33], 0, s[34:35]
	s_waitcnt lgkmcnt(0)
	s_barrier
	s_cbranch_scc1 .Lattn_stag_out
	v_mov_b32_e32 v157, v96
	s_mov_b32 s81, s14
	s_mov_b32 s14, s78
	s_mov_b32 s78, s1
	v_mov_b32_e32 v165, v37
	s_branch .LBB0_574
.Lattn_stag_out:
	s_andn2_b64 vcc, exec, s[76:77]
	s_cbranch_vccnz .LBB0_584
	s_barrier
	s_branch .LBB0_584
